# hand-written SwiGLU epilogue of the FFN gate/up GEMM (packed f32 math, no hazard nops) + barrier census loads issued back-to-back
# baseline (speedup 1.0000x reference)
.LBB0_1022:
	s_mov_b32 s100, 15
	s_add_i32 m0, s60, 0x18000
	v_lshl_add_u64 v[2:3], v[2:3], 0, s[82:83]
	v_and_b32_e32 v21, 15, v19
	s_waitcnt vmcnt(4)
	s_barrier
	global_load_lds_dwordx4 v[2:3], off
	v_lshl_add_u64 v[2:3], v[4:5], 0, s[82:83]
	s_add_i32 m0, s60, 0x1a000
	s_add_i32 s78, s60, 0x8000
	v_lshl_or_b32 v143, s23, 6, v21
	global_load_lds_dwordx4 v[2:3], off
	v_lshl_add_u64 v[2:3], v[6:7], 0, s[82:83]
	s_mov_b32 m0, s78
	s_add_i32 s23, s60, 0xa000
	global_load_lds_dwordx4 v[2:3], off
	v_lshl_add_u64 v[2:3], v[8:9], 0, s[82:83]
	s_mov_b32 m0, s23
	v_bfe_u32 v20, v19, 4, 2
	global_load_lds_dwordx4 v[2:3], off
	s_add_i32 m0, s60, 0x1c000
	v_lshl_add_u64 v[2:3], v[10:11], 0, s[82:83]
	global_load_lds_dwordx4 v[2:3], off
	v_lshl_add_u64 v[2:3], v[12:13], 0, s[82:83]
	s_add_i32 m0, s60, 0x1e000
	v_lshlrev_b32_e32 v19, 2, v19
	global_load_lds_dwordx4 v[2:3], off
	v_lshlrev_b32_e32 v22, 4, v20
	v_lshlrev_b32_e32 v21, 6, v21
	v_and_b32_e32 v19, 32, v19
	s_and_b32 s30, s1, 3
	s_lshr_b32 s34, s0, 6
	v_or_b32_e32 v23, v21, v22
	v_lshlrev_b32_e32 v24, 7, v143
	v_bitop3_b32 v21, v21, v19, v22 bitop3:0x36
	s_movk_i32 s0, 0xe000
	v_and_or_b32 v21, v24, s0, v21
	s_lshl_b32 s0, s30, 12
	s_xor_b64 s[4:5], s[20:21], -1
	v_bitop3_b32 v217, v23, s0, v19 bitop3:0xde
	s_add_i32 s73, s34, -2
	s_ashr_i32 s49, s79, 31
	s_ashr_i32 s50, s48, 31
	s_mul_i32 s0, s29, 6
	s_lshl_b32 s35, s29, 3
	v_and_b32_e32 v142, 0x6780, v24
	v_writelane_b32 v249, s0, 61
	s_and_b64 s[0:1], s[20:21], exec
	v_readlane_b32 s20, v251, 53
	v_lshlrev_b32_e32 v2, 2, v142
	v_mov_b32_e32 v3, v1
	v_readlane_b32 s21, v251, 54
	s_movk_i32 s0, 0x5000
	v_writelane_b32 v248, s4, 0
	v_lshl_add_u64 v[144:145], s[20:21], 0, v[2:3]
	v_cvt_f32_ubyte0_e32 v2, s35
	v_rcp_iflag_f32_e32 v2, v2
	v_writelane_b32 v248, s5, 1
	v_readlane_b32 s4, v249, 47
	s_cselect_b32 s0, 0x2000, s0
	v_mul_f32_e32 v2, 0x4f7ffffe, v2
	v_cvt_u32_f32_e32 v2, v2
	v_readlane_b32 s5, v249, 48
	s_cmp_lt_i32 s4, 1
	v_readlane_b32 s20, v251, 5
	s_cselect_b64 s[4:5], -1, 0
	v_readlane_b32 s21, v251, 6
	s_add_u32 s0, s20, s0
	v_writelane_b32 v248, s0, 2
	s_addc_u32 s0, s21, 0
	v_writelane_b32 v248, s0, 3
	s_sub_i32 s0, 0, s35
	v_readfirstlane_b32 s1, v2
	s_mul_i32 s0, s0, s1
	v_writelane_b32 v249, s4, 58
	s_mul_hi_u32 s0, s1, s0
	v_add_u32_e32 v0, v15, v0
	s_waitcnt vmcnt(6)
	v_writelane_b32 v249, s5, 59
	s_add_i32 s0, s1, s0
	v_add_lshl_u32 v2, v0, v14, 1
	v_add_u32_e32 v0, v18, v16
	v_lshlrev_b32_e32 v4, 2, v20
	s_mov_b32 s47, s75
	v_writelane_b32 v249, s0, 62
	v_lshl_add_u64 v[146:147], s[74:75], 0, v[2:3]
	v_add_lshl_u32 v2, v0, v17, 1
	v_lshl_or_b32 v218, s30, 5, v4
	s_mov_b32 s29, 0
	v_lshl_or_b32 v219, s30, 4, v4
	v_lshl_add_u64 v[148:149], s[74:75], 0, v[2:3]
	v_add_u32_e32 v220, 0x50, v21
	v_writelane_b32 v249, s46, 56
	s_barrier
	s_nop 0
	v_writelane_b32 v249, s47, 57
	s_branch .LBB0_1025

.LBB0_1276:
	s_and_b64 vcc, exec, s[0:1]
	s_cbranch_vccz .LBB0_1278
	v_readlane_b32 s0, v251, 29
	v_readlane_b32 s1, v251, 30
	v_add_u32_e32 v0, s24, v143
	v_lshl_or_b32 v150, s42, 7, v219
	v_mul_u32_u24_e32 v0, 0x1600, v0
	v_lshl_add_u32 v150, v150, 1, v0
	v_mov_b32_e32 v130, 0xbfb8aa3b
	v_mov_b32_e32 v131, 0xbfb8aa3b
	v_mov_b32_e32 v132, 1.0
	v_mov_b32_e32 v133, 1.0
	s_bitcmp1_b32 s100, 0
	s_cbranch_scc0 .Lq_epi0
	v_pk_mul_f32 v[154:155], v[126:127], v[130:131]
	v_pk_mul_f32 v[156:157], v[128:129], v[130:131]
	v_pk_mul_f32 v[126:127], v[126:127], v[122:123]
	v_pk_mul_f32 v[128:129], v[128:129], v[124:125]
	v_exp_f32_e32 v154, v154
	v_exp_f32_e32 v155, v155
	v_exp_f32_e32 v156, v156
	v_exp_f32_e32 v157, v157
	v_pk_add_f32 v[154:155], v[154:155], v[132:133]
	v_pk_add_f32 v[156:157], v[156:157], v[132:133]
	v_rcp_f32_e32 v154, v154
	v_rcp_f32_e32 v155, v155
	v_rcp_f32_e32 v156, v156
	v_rcp_f32_e32 v157, v157
	v_pk_mul_f32 v[126:127], v[126:127], v[154:155]
	v_pk_mul_f32 v[128:129], v[128:129], v[156:157]
	v_add_u32_e32 v151, 0x0, v150
	v_cvt_pk_bf16_f32 v122, v126, v127
	v_cvt_pk_bf16_f32 v123, v128, v129
	global_store_dwordx2 v151, v[122:123], s[0:1]
	v_pk_mul_f32 v[158:159], v[118:119], v[130:131]
	v_pk_mul_f32 v[160:161], v[120:121], v[130:131]
	v_pk_mul_f32 v[118:119], v[118:119], v[114:115]
	v_pk_mul_f32 v[120:121], v[120:121], v[116:117]
	v_exp_f32_e32 v158, v158
	v_exp_f32_e32 v159, v159
	v_exp_f32_e32 v160, v160
	v_exp_f32_e32 v161, v161
	v_pk_add_f32 v[158:159], v[158:159], v[132:133]
	v_pk_add_f32 v[160:161], v[160:161], v[132:133]
	v_rcp_f32_e32 v158, v158
	v_rcp_f32_e32 v159, v159
	v_rcp_f32_e32 v160, v160
	v_rcp_f32_e32 v161, v161
	v_pk_mul_f32 v[118:119], v[118:119], v[158:159]
	v_pk_mul_f32 v[120:121], v[120:121], v[160:161]
	v_add_u32_e32 v152, 0x16000, v150
	v_cvt_pk_bf16_f32 v114, v118, v119
	v_cvt_pk_bf16_f32 v115, v120, v121
	global_store_dwordx2 v152, v[114:115], s[0:1]
	v_pk_mul_f32 v[154:155], v[110:111], v[130:131]
	v_pk_mul_f32 v[156:157], v[112:113], v[130:131]
	v_pk_mul_f32 v[110:111], v[110:111], v[106:107]
	v_pk_mul_f32 v[112:113], v[112:113], v[108:109]
	v_exp_f32_e32 v154, v154
	v_exp_f32_e32 v155, v155
	v_exp_f32_e32 v156, v156
	v_exp_f32_e32 v157, v157
	v_pk_add_f32 v[154:155], v[154:155], v[132:133]
	v_pk_add_f32 v[156:157], v[156:157], v[132:133]
	v_rcp_f32_e32 v154, v154
	v_rcp_f32_e32 v155, v155
	v_rcp_f32_e32 v156, v156
	v_rcp_f32_e32 v157, v157
	v_pk_mul_f32 v[110:111], v[110:111], v[154:155]
	v_pk_mul_f32 v[112:113], v[112:113], v[156:157]
	v_add_u32_e32 v151, 0x2c000, v150
	v_cvt_pk_bf16_f32 v106, v110, v111
	v_cvt_pk_bf16_f32 v107, v112, v113
	global_store_dwordx2 v151, v[106:107], s[0:1]
	v_pk_mul_f32 v[158:159], v[102:103], v[130:131]
	v_pk_mul_f32 v[160:161], v[104:105], v[130:131]
	v_pk_mul_f32 v[102:103], v[102:103], v[98:99]
	v_pk_mul_f32 v[104:105], v[104:105], v[100:101]
	v_exp_f32_e32 v158, v158
	v_exp_f32_e32 v159, v159
	v_exp_f32_e32 v160, v160
	v_exp_f32_e32 v161, v161
	v_pk_add_f32 v[158:159], v[158:159], v[132:133]
	v_pk_add_f32 v[160:161], v[160:161], v[132:133]
	v_rcp_f32_e32 v158, v158
	v_rcp_f32_e32 v159, v159
	v_rcp_f32_e32 v160, v160
	v_rcp_f32_e32 v161, v161
	v_pk_mul_f32 v[102:103], v[102:103], v[158:159]
	v_pk_mul_f32 v[104:105], v[104:105], v[160:161]
	v_add_u32_e32 v152, 0x42000, v150
	v_cvt_pk_bf16_f32 v98, v102, v103
	v_cvt_pk_bf16_f32 v99, v104, v105
	global_store_dwordx2 v152, v[98:99], s[0:1]
.Lq_epi0:
	s_bitcmp1_b32 s100, 1
	s_cbranch_scc0 .Lq_epi1
	v_pk_mul_f32 v[154:155], v[62:63], v[130:131]
	v_pk_mul_f32 v[156:157], v[64:65], v[130:131]
	v_pk_mul_f32 v[62:63], v[62:63], v[58:59]
	v_pk_mul_f32 v[64:65], v[64:65], v[60:61]
	v_exp_f32_e32 v154, v154
	v_exp_f32_e32 v155, v155
	v_exp_f32_e32 v156, v156
	v_exp_f32_e32 v157, v157
	v_pk_add_f32 v[154:155], v[154:155], v[132:133]
	v_pk_add_f32 v[156:157], v[156:157], v[132:133]
	v_rcp_f32_e32 v154, v154
	v_rcp_f32_e32 v155, v155
	v_rcp_f32_e32 v156, v156
	v_rcp_f32_e32 v157, v157
	v_pk_mul_f32 v[62:63], v[62:63], v[154:155]
	v_pk_mul_f32 v[64:65], v[64:65], v[156:157]
	v_add_u32_e32 v151, 0x0, v150
	v_cvt_pk_bf16_f32 v58, v62, v63
	v_cvt_pk_bf16_f32 v59, v64, v65
	global_store_dwordx2 v151, v[58:59], s[0:1] offset:128
	v_pk_mul_f32 v[158:159], v[54:55], v[130:131]
	v_pk_mul_f32 v[160:161], v[56:57], v[130:131]
	v_pk_mul_f32 v[54:55], v[54:55], v[50:51]
	v_pk_mul_f32 v[56:57], v[56:57], v[52:53]
	v_exp_f32_e32 v158, v158
	v_exp_f32_e32 v159, v159
	v_exp_f32_e32 v160, v160
	v_exp_f32_e32 v161, v161
	v_pk_add_f32 v[158:159], v[158:159], v[132:133]
	v_pk_add_f32 v[160:161], v[160:161], v[132:133]
	v_rcp_f32_e32 v158, v158
	v_rcp_f32_e32 v159, v159
	v_rcp_f32_e32 v160, v160
	v_rcp_f32_e32 v161, v161
	v_pk_mul_f32 v[54:55], v[54:55], v[158:159]
	v_pk_mul_f32 v[56:57], v[56:57], v[160:161]
	v_add_u32_e32 v152, 0x16000, v150
	v_cvt_pk_bf16_f32 v50, v54, v55
	v_cvt_pk_bf16_f32 v51, v56, v57
	global_store_dwordx2 v152, v[50:51], s[0:1] offset:128
	v_pk_mul_f32 v[154:155], v[46:47], v[130:131]
	v_pk_mul_f32 v[156:157], v[48:49], v[130:131]
	v_pk_mul_f32 v[46:47], v[46:47], v[42:43]
	v_pk_mul_f32 v[48:49], v[48:49], v[44:45]
	v_exp_f32_e32 v154, v154
	v_exp_f32_e32 v155, v155
	v_exp_f32_e32 v156, v156
	v_exp_f32_e32 v157, v157
	v_pk_add_f32 v[154:155], v[154:155], v[132:133]
	v_pk_add_f32 v[156:157], v[156:157], v[132:133]
	v_rcp_f32_e32 v154, v154
	v_rcp_f32_e32 v155, v155
	v_rcp_f32_e32 v156, v156
	v_rcp_f32_e32 v157, v157
	v_pk_mul_f32 v[46:47], v[46:47], v[154:155]
	v_pk_mul_f32 v[48:49], v[48:49], v[156:157]
	v_add_u32_e32 v151, 0x2c000, v150
	v_cvt_pk_bf16_f32 v42, v46, v47
	v_cvt_pk_bf16_f32 v43, v48, v49
	global_store_dwordx2 v151, v[42:43], s[0:1] offset:128
	v_pk_mul_f32 v[158:159], v[38:39], v[130:131]
	v_pk_mul_f32 v[160:161], v[40:41], v[130:131]
	v_pk_mul_f32 v[38:39], v[38:39], v[34:35]
	v_pk_mul_f32 v[40:41], v[40:41], v[36:37]
	v_exp_f32_e32 v158, v158
	v_exp_f32_e32 v159, v159
	v_exp_f32_e32 v160, v160
	v_exp_f32_e32 v161, v161
	v_pk_add_f32 v[158:159], v[158:159], v[132:133]
	v_pk_add_f32 v[160:161], v[160:161], v[132:133]
	v_rcp_f32_e32 v158, v158
	v_rcp_f32_e32 v159, v159
	v_rcp_f32_e32 v160, v160
	v_rcp_f32_e32 v161, v161
	v_pk_mul_f32 v[38:39], v[38:39], v[158:159]
	v_pk_mul_f32 v[40:41], v[40:41], v[160:161]
	v_add_u32_e32 v152, 0x42000, v150
	v_cvt_pk_bf16_f32 v34, v38, v39
	v_cvt_pk_bf16_f32 v35, v40, v41
	global_store_dwordx2 v152, v[34:35], s[0:1] offset:128
.Lq_epi1:
	s_bitcmp1_b32 s100, 2
	s_cbranch_scc0 .Lq_epi2
	v_pk_mul_f32 v[154:155], v[94:95], v[130:131]
	v_pk_mul_f32 v[156:157], v[96:97], v[130:131]
	v_pk_mul_f32 v[94:95], v[94:95], v[90:91]
	v_pk_mul_f32 v[96:97], v[96:97], v[92:93]
	v_exp_f32_e32 v154, v154
	v_exp_f32_e32 v155, v155
	v_exp_f32_e32 v156, v156
	v_exp_f32_e32 v157, v157
	v_pk_add_f32 v[154:155], v[154:155], v[132:133]
	v_pk_add_f32 v[156:157], v[156:157], v[132:133]
	v_rcp_f32_e32 v154, v154
	v_rcp_f32_e32 v155, v155
	v_rcp_f32_e32 v156, v156
	v_rcp_f32_e32 v157, v157
	v_pk_mul_f32 v[94:95], v[94:95], v[154:155]
	v_pk_mul_f32 v[96:97], v[96:97], v[156:157]
	v_add_u32_e32 v151, 0xb0000, v150
	v_cvt_pk_bf16_f32 v90, v94, v95
	v_cvt_pk_bf16_f32 v91, v96, v97
	global_store_dwordx2 v151, v[90:91], s[0:1]
	v_pk_mul_f32 v[158:159], v[86:87], v[130:131]
	v_pk_mul_f32 v[160:161], v[88:89], v[130:131]
	v_pk_mul_f32 v[86:87], v[86:87], v[82:83]
	v_pk_mul_f32 v[88:89], v[88:89], v[84:85]
	v_exp_f32_e32 v158, v158
	v_exp_f32_e32 v159, v159
	v_exp_f32_e32 v160, v160
	v_exp_f32_e32 v161, v161
	v_pk_add_f32 v[158:159], v[158:159], v[132:133]
	v_pk_add_f32 v[160:161], v[160:161], v[132:133]
	v_rcp_f32_e32 v158, v158
	v_rcp_f32_e32 v159, v159
	v_rcp_f32_e32 v160, v160
	v_rcp_f32_e32 v161, v161
	v_pk_mul_f32 v[86:87], v[86:87], v[158:159]
	v_pk_mul_f32 v[88:89], v[88:89], v[160:161]
	v_add_u32_e32 v152, 0xc6000, v150
	v_cvt_pk_bf16_f32 v82, v86, v87
	v_cvt_pk_bf16_f32 v83, v88, v89
	global_store_dwordx2 v152, v[82:83], s[0:1]
	v_pk_mul_f32 v[154:155], v[78:79], v[130:131]
	v_pk_mul_f32 v[156:157], v[80:81], v[130:131]
	v_pk_mul_f32 v[78:79], v[78:79], v[74:75]
	v_pk_mul_f32 v[80:81], v[80:81], v[76:77]
	v_exp_f32_e32 v154, v154
	v_exp_f32_e32 v155, v155
	v_exp_f32_e32 v156, v156
	v_exp_f32_e32 v157, v157
	v_pk_add_f32 v[154:155], v[154:155], v[132:133]
	v_pk_add_f32 v[156:157], v[156:157], v[132:133]
	v_rcp_f32_e32 v154, v154
	v_rcp_f32_e32 v155, v155
	v_rcp_f32_e32 v156, v156
	v_rcp_f32_e32 v157, v157
	v_pk_mul_f32 v[78:79], v[78:79], v[154:155]
	v_pk_mul_f32 v[80:81], v[80:81], v[156:157]
	v_add_u32_e32 v151, 0xdc000, v150
	v_cvt_pk_bf16_f32 v74, v78, v79
	v_cvt_pk_bf16_f32 v75, v80, v81
	global_store_dwordx2 v151, v[74:75], s[0:1]
	v_pk_mul_f32 v[158:159], v[70:71], v[130:131]
	v_pk_mul_f32 v[160:161], v[72:73], v[130:131]
	v_pk_mul_f32 v[70:71], v[70:71], v[66:67]
	v_pk_mul_f32 v[72:73], v[72:73], v[68:69]
	v_exp_f32_e32 v158, v158
	v_exp_f32_e32 v159, v159
	v_exp_f32_e32 v160, v160
	v_exp_f32_e32 v161, v161
	v_pk_add_f32 v[158:159], v[158:159], v[132:133]
	v_pk_add_f32 v[160:161], v[160:161], v[132:133]
	v_rcp_f32_e32 v158, v158
	v_rcp_f32_e32 v159, v159
	v_rcp_f32_e32 v160, v160
	v_rcp_f32_e32 v161, v161
	v_pk_mul_f32 v[70:71], v[70:71], v[158:159]
	v_pk_mul_f32 v[72:73], v[72:73], v[160:161]
	v_add_u32_e32 v152, 0xf2000, v150
	v_cvt_pk_bf16_f32 v66, v70, v71
	v_cvt_pk_bf16_f32 v67, v72, v73
	global_store_dwordx2 v152, v[66:67], s[0:1]
.Lq_epi2:
	s_bitcmp1_b32 s100, 3
	s_cbranch_scc0 .Lq_epi3
	v_pk_mul_f32 v[154:155], v[30:31], v[130:131]
	v_pk_mul_f32 v[156:157], v[32:33], v[130:131]
	v_pk_mul_f32 v[30:31], v[30:31], v[26:27]
	v_pk_mul_f32 v[32:33], v[32:33], v[28:29]
	v_exp_f32_e32 v154, v154
	v_exp_f32_e32 v155, v155
	v_exp_f32_e32 v156, v156
	v_exp_f32_e32 v157, v157
	v_pk_add_f32 v[154:155], v[154:155], v[132:133]
	v_pk_add_f32 v[156:157], v[156:157], v[132:133]
	v_rcp_f32_e32 v154, v154
	v_rcp_f32_e32 v155, v155
	v_rcp_f32_e32 v156, v156
	v_rcp_f32_e32 v157, v157
	v_pk_mul_f32 v[30:31], v[30:31], v[154:155]
	v_pk_mul_f32 v[32:33], v[32:33], v[156:157]
	v_add_u32_e32 v151, 0xb0000, v150
	v_cvt_pk_bf16_f32 v26, v30, v31
	v_cvt_pk_bf16_f32 v27, v32, v33
	global_store_dwordx2 v151, v[26:27], s[0:1] offset:128
	v_pk_mul_f32 v[158:159], v[22:23], v[130:131]
	v_pk_mul_f32 v[160:161], v[24:25], v[130:131]
	v_pk_mul_f32 v[22:23], v[22:23], v[18:19]
	v_pk_mul_f32 v[24:25], v[24:25], v[20:21]
	v_exp_f32_e32 v158, v158
	v_exp_f32_e32 v159, v159
	v_exp_f32_e32 v160, v160
	v_exp_f32_e32 v161, v161
	v_pk_add_f32 v[158:159], v[158:159], v[132:133]
	v_pk_add_f32 v[160:161], v[160:161], v[132:133]
	v_rcp_f32_e32 v158, v158
	v_rcp_f32_e32 v159, v159
	v_rcp_f32_e32 v160, v160
	v_rcp_f32_e32 v161, v161
	v_pk_mul_f32 v[22:23], v[22:23], v[158:159]
	v_pk_mul_f32 v[24:25], v[24:25], v[160:161]
	v_add_u32_e32 v152, 0xc6000, v150
	v_cvt_pk_bf16_f32 v18, v22, v23
	v_cvt_pk_bf16_f32 v19, v24, v25
	global_store_dwordx2 v152, v[18:19], s[0:1] offset:128
	v_pk_mul_f32 v[154:155], v[14:15], v[130:131]
	v_pk_mul_f32 v[156:157], v[16:17], v[130:131]
	v_pk_mul_f32 v[14:15], v[14:15], v[10:11]
	v_pk_mul_f32 v[16:17], v[16:17], v[12:13]
	v_exp_f32_e32 v154, v154
	v_exp_f32_e32 v155, v155
	v_exp_f32_e32 v156, v156
	v_exp_f32_e32 v157, v157
	v_pk_add_f32 v[154:155], v[154:155], v[132:133]
	v_pk_add_f32 v[156:157], v[156:157], v[132:133]
	v_rcp_f32_e32 v154, v154
	v_rcp_f32_e32 v155, v155
	v_rcp_f32_e32 v156, v156
	v_rcp_f32_e32 v157, v157
	v_pk_mul_f32 v[14:15], v[14:15], v[154:155]
	v_pk_mul_f32 v[16:17], v[16:17], v[156:157]
	v_add_u32_e32 v151, 0xdc000, v150
	v_cvt_pk_bf16_f32 v10, v14, v15
	v_cvt_pk_bf16_f32 v11, v16, v17
	global_store_dwordx2 v151, v[10:11], s[0:1] offset:128
	v_pk_mul_f32 v[158:159], v[6:7], v[130:131]
	v_pk_mul_f32 v[160:161], v[8:9], v[130:131]
	v_pk_mul_f32 v[6:7], v[6:7], v[2:3]
	v_pk_mul_f32 v[8:9], v[8:9], v[4:5]
	v_exp_f32_e32 v158, v158
	v_exp_f32_e32 v159, v159
	v_exp_f32_e32 v160, v160
	v_exp_f32_e32 v161, v161
	v_pk_add_f32 v[158:159], v[158:159], v[132:133]
	v_pk_add_f32 v[160:161], v[160:161], v[132:133]
	v_rcp_f32_e32 v158, v158
	v_rcp_f32_e32 v159, v159
	v_rcp_f32_e32 v160, v160
	v_rcp_f32_e32 v161, v161
	v_pk_mul_f32 v[6:7], v[6:7], v[158:159]
	v_pk_mul_f32 v[8:9], v[8:9], v[160:161]
	v_add_u32_e32 v152, 0xf2000, v150
	v_cvt_pk_bf16_f32 v2, v6, v7
	v_cvt_pk_bf16_f32 v3, v8, v9
	global_store_dwordx2 v152, v[2:3], s[0:1] offset:128
.Lq_epi3:
.LBB0_1278:
	s_mov_b64 s[0:1], 0

.LBB0_1897:
	v_readlane_b32 s20, v252, 3
	v_readlane_b32 s21, v252, 4
	s_mov_b64 s[24:25], -1
	s_nop 3
	global_load_dword v0, v1, s[20:21] sc1
	v_readlane_b32 s20, v252, 5
	v_readlane_b32 s21, v252, 6
	s_waitcnt lgkmcnt(0)
	s_nop 3
	global_load_dword v2, v1, s[20:21] sc1
	v_readlane_b32 s20, v252, 7
	v_readlane_b32 s21, v252, 8
	s_nop 1
	s_nop 2
	global_load_dword v3, v1, s[20:21] sc1
	v_readlane_b32 s20, v252, 9
	v_readlane_b32 s21, v252, 10
	s_nop 1
	s_nop 2
	global_load_dword v4, v1, s[20:21] sc1
	v_readlane_b32 s20, v252, 11
	v_readlane_b32 s21, v252, 12
	s_nop 1
	s_nop 2
	global_load_dword v5, v1, s[20:21] sc1
	v_readlane_b32 s20, v252, 13
	v_readlane_b32 s21, v252, 14
	s_nop 1
	s_nop 2
	global_load_dword v6, v1, s[20:21] sc1
	v_readlane_b32 s20, v252, 15
	v_readlane_b32 s21, v252, 16
	s_nop 1
	s_nop 2
	global_load_dword v7, v1, s[20:21] sc1
	v_readlane_b32 s20, v252, 17
	v_readlane_b32 s21, v252, 18
	s_nop 1
	s_nop 2
	global_load_dword v8, v1, s[20:21] sc1
	v_readlane_b32 s20, v252, 19
	v_readlane_b32 s21, v252, 20
	s_nop 1
	s_nop 2
	global_load_dword v9, v1, s[20:21] sc1
	v_readlane_b32 s20, v252, 21
	v_readlane_b32 s21, v252, 22
	s_nop 1
	s_nop 2
	global_load_dword v10, v1, s[20:21] sc1
	v_readlane_b32 s20, v252, 23
	v_readlane_b32 s21, v252, 24
	s_nop 1
	s_nop 2
	global_load_dword v11, v1, s[20:21] sc1
	v_readlane_b32 s20, v252, 25
	v_readlane_b32 s21, v252, 26
	s_nop 1
	s_nop 2
	global_load_dword v12, v1, s[20:21] sc1
	v_readlane_b32 s20, v252, 27
	v_readlane_b32 s21, v252, 28
	s_nop 1
	s_nop 2
	global_load_dword v13, v1, s[20:21] sc1
	v_readlane_b32 s20, v252, 29
	v_readlane_b32 s21, v252, 30
	s_nop 1
	s_nop 2
	global_load_dword v14, v1, s[20:21] sc1
	v_readlane_b32 s20, v252, 31
	v_readlane_b32 s21, v252, 32
	s_nop 1
	s_nop 2
	global_load_dword v15, v1, s[20:21] sc1
	v_readlane_b32 s20, v252, 33
	v_readlane_b32 s21, v252, 34
	s_nop 1
	s_nop 2
	global_load_dword v16, v1, s[20:21] sc1
	s_mov_b64 s[20:21], -1
	s_waitcnt vmcnt(0)
	v_add_u32_e32 v17, v2, v0
	v_add_u32_e32 v17, v17, v3
	v_add_u32_e32 v17, v17, v4
	v_add_u32_e32 v17, v17, v5
	v_add_u32_e32 v17, v17, v6
	v_add_u32_e32 v17, v17, v7
	v_add_u32_e32 v17, v17, v8
	v_add_u32_e32 v17, v17, v9
	v_add_u32_e32 v17, v17, v10
	v_add_u32_e32 v17, v17, v11
	v_add_u32_e32 v17, v17, v12
	v_add_u32_e32 v17, v17, v13
	v_add_u32_e32 v17, v17, v14
	v_add_u32_e32 v17, v17, v15
	v_add_u32_e32 v17, v17, v16
	v_cmp_eq_u32_e32 vcc, s23, v17
	s_cbranch_vccnz .LBB0_1896
	s_and_b32 s20, s26, 0xff
	s_cmp_eq_u32 s20, 0
	s_mov_b64 s[20:21], -1
	s_mov_b64 s[36:37], -1
	s_sleep 1
	s_cbranch_scc1 .LBB0_1901
	s_and_b64 vcc, exec, s[36:37]
	s_cbranch_vccz .LBB0_1896

	.amdhsa_kernel _Z2mk6Paramsii
		.amdhsa_group_segment_fixed_size 80
		.amdhsa_private_segment_fixed_size 0
		.amdhsa_kernarg_size 616
		.amdhsa_user_sgpr_count 2
		.amdhsa_user_sgpr_dispatch_ptr 0
		.amdhsa_user_sgpr_queue_ptr 0
		.amdhsa_user_sgpr_kernarg_segment_ptr 1
		.amdhsa_user_sgpr_dispatch_id 0
		.amdhsa_user_sgpr_kernarg_preload_length 0
		.amdhsa_user_sgpr_kernarg_preload_offset 0
		.amdhsa_user_sgpr_private_segment_size 0
		.amdhsa_uses_dynamic_stack 0
		.amdhsa_enable_private_segment 0
		.amdhsa_system_sgpr_workgroup_id_x 1
		.amdhsa_system_sgpr_workgroup_id_y 0
		.amdhsa_system_sgpr_workgroup_id_z 0
		.amdhsa_system_sgpr_workgroup_info 0
		.amdhsa_system_vgpr_workitem_id 2
		.amdhsa_next_free_vgpr 253
		.amdhsa_next_free_sgpr 102
		.amdhsa_accum_offset 256
		.amdhsa_reserve_vcc 1
		.amdhsa_float_round_mode_32 0
		.amdhsa_float_round_mode_16_64 0
		.amdhsa_float_denorm_mode_32 3
		.amdhsa_float_denorm_mode_16_64 3
		.amdhsa_dx10_clamp 1
		.amdhsa_ieee_mode 1
		.amdhsa_fp16_overflow 0
		.amdhsa_tg_split 0
		.amdhsa_exception_fp_ieee_invalid_op 0
		.amdhsa_exception_fp_denorm_src 0
		.amdhsa_exception_fp_ieee_div_zero 0
		.amdhsa_exception_fp_ieee_overflow 0
		.amdhsa_exception_fp_ieee_underflow 0
		.amdhsa_exception_fp_ieee_inexact 0
		.amdhsa_exception_int_div_zero 0
	.end_amdhsa_kernel

amdhsa.kernels:
  - .agpr_count:     0
    .args:
      - .offset:         0
        .size:           352
        .value_kind:     by_value
      - .offset:         352
        .size:           4
        .value_kind:     by_value
      - .offset:         356
        .size:           4
        .value_kind:     by_value
      - .offset:         360
        .size:           4
        .value_kind:     hidden_block_count_x
      - .offset:         364
        .size:           4
        .value_kind:     hidden_block_count_y
      - .offset:         368
        .size:           4
        .value_kind:     hidden_block_count_z
      - .offset:         372
        .size:           2
        .value_kind:     hidden_group_size_x
      - .offset:         374
        .size:           2
        .value_kind:     hidden_group_size_y
      - .offset:         376
        .size:           2
        .value_kind:     hidden_group_size_z
      - .offset:         378
        .size:           2
        .value_kind:     hidden_remainder_x
      - .offset:         380
        .size:           2
        .value_kind:     hidden_remainder_y
      - .offset:         382
        .size:           2
        .value_kind:     hidden_remainder_z
      - .offset:         400
        .size:           8
        .value_kind:     hidden_global_offset_x
      - .offset:         408
        .size:           8
        .value_kind:     hidden_global_offset_y
      - .offset:         416
        .size:           8
        .value_kind:     hidden_global_offset_z
      - .offset:         424
        .size:           2
        .value_kind:     hidden_grid_dims
      - .offset:         448
        .size:           8
        .value_kind:     hidden_multigrid_sync_arg
      - .offset:         480
        .size:           4
        .value_kind:     hidden_dynamic_lds_size
    .group_segment_fixed_size: 80
    .kernarg_segment_align: 8
    .kernarg_segment_size: 616
    .language:       OpenCL C
    .language_version:
      - 2
      - 0
    .max_flat_workgroup_size: 512
    .name:           _Z2mk6Paramsii
    .private_segment_fixed_size: 0
    .sgpr_count:     108
    .sgpr_spill_count: 324
    .symbol:         _Z2mk6Paramsii.kd
    .uniform_work_group_size: 1
    .uses_dynamic_stack: false
    .vgpr_count:     253
    .vgpr_spill_count: 0
    .wavefront_size: 64
